# HGRN output units: next queue item claimed behind the MFMA stream (older than the epilogue stores, so the loop top waits with a count instead of draining them)
# speedup vs baseline: 1.0195x; 1.0003x over previous
; #define LAS __attribute__((address_space(3)))
; DEV unsigned xb_ld(unsigned* p)              { return __hip_atomic_load(p, __ATOMIC_RELAXED, __HIP_MEMORY_SCOPE_AGENT); }
; template <class Tp> DEV Tp* wsp(const Frame& F, size_t off) { return (Tp*)(F.ws + off); }
; DEV void p3_phase(Frame& F, bool do_scan, int qoff) {
;     ...
;     {
;         LAS int* qslot = (LAS int*)(F.lds + LDSCTL_OFF + 32); unsigned* cctr = (unsigned*)(F.ws + WS_CTL) + CTL_Q + 448 + (qoff ? 32 : 0);
;         bool ready = false;
;         for (;;) {
;             if (F.tid == 0) *qslot = (int)atomicAdd(cctr, 1u);
;             __syncthreads();
;             const int item = *qslot;
;             __syncthreads();
;             if (item >= 512) break;
;             if (!ready) {
;                 if (F.tid == 0) { unsigned sp = 0u; while (xb_ld(scan_done) < 64u) { __builtin_amdgcn_s_sleep(2); if (++sp > (1u << 22)) break; }
;                     __builtin_amdgcn_fence(__ATOMIC_ACQUIRE, "agent"); asm volatile("s_waitcnt vmcnt(0)" ::: "memory"); }
;                 __syncthreads(); ready = true;
;             }
;             hgrn_c_unit(F, item >> 1, item & 1);
;         }
; DEV void hgrn_c_unit(Frame& F, int c, int hp) {
;     ...
;     const bf16* HG = wsp<bf16>(F, WS_HG) + row * 512 + h * 128 + 4 * q4; bf16* OB = wsp<bf16>(F, WS_OB) + row * 512 + h * 128 + 4 * q4; const float* gn = ((const float*)F.A.in[20]) + 4 * q4;
; #pragma unroll
;     for (int vt = 0; vt < 8; ++vt) { const v2u gw_ = *(const v2u*)(HG + 16 * vt); const f32x4 g4 = *(const f32x4*)(gn + 16 * vt);
.LBB0_1683:
	v_lshlrev_b32_e32 v2, 4, v138
	v_and_b32_e32 v3, 0xf0, v2
	v_lshrrev_b32_e32 v2, 4, v138
	v_bfe_u32 v4, v138, 4, 7
	v_and_b32_e32 v2, 0x7ffff80, v2
	s_movk_i32 s2, 0x120
	v_mul_lo_u32 v2, v2, s2
	v_mul_u32_u24_e32 v4, 0x120, v4
	v_add3_u32 v5, 0, v2, v4
	v_add_u32_e32 v2, 0x200, v138
	v_lshrrev_b32_e32 v6, 4, v2
	v_lshlrev_b32_e32 v36, 3, v2
	v_bfe_u32 v2, v2, 4, 7
	v_and_b32_e32 v6, 0x7ffff80, v6
	v_mul_lo_u32 v6, v6, s2
	v_mul_u32_u24_e32 v2, 0x120, v2
	v_add3_u32 v6, 0, v6, v2
	v_add_u32_e32 v2, 0x400, v138
	v_lshrrev_b32_e32 v7, 4, v2
	v_lshlrev_b32_e32 v38, 3, v2
	v_bfe_u32 v2, v2, 4, 7
	v_and_b32_e32 v7, 0x7ffff80, v7
	v_mul_lo_u32 v7, v7, s2
	v_mul_u32_u24_e32 v2, 0x120, v2
	v_add3_u32 v7, 0, v7, v2
	v_add_u32_e32 v2, 0x600, v138
	v_lshrrev_b32_e32 v8, 4, v2
	v_lshlrev_b32_e32 v40, 3, v2
	v_bfe_u32 v2, v2, 4, 7
	v_and_b32_e32 v8, 0x7ffff80, v8
	v_mul_lo_u32 v8, v8, s2
	v_mul_u32_u24_e32 v2, 0x120, v2
	v_add3_u32 v8, 0, v8, v2
	v_add_u32_e32 v2, 0x800, v138
	v_lshlrev_b32_e32 v42, 3, v2
	v_lshrrev_b32_e32 v2, 4, v2
	v_and_b32_e32 v2, 0x7ffff80, v2
	v_mul_lo_u32 v2, v2, s2
	v_add3_u32 v4, 0, v2, v4
	v_add_u32_e32 v2, 0xa00, v138
	v_lshrrev_b32_e32 v9, 4, v2
	v_lshlrev_b32_e32 v44, 3, v2
	v_bfe_u32 v2, v2, 4, 7
	v_and_b32_e32 v9, 0x7ffff80, v9
	v_mul_lo_u32 v9, v9, s2
	v_mul_u32_u24_e32 v2, 0x120, v2
	v_add3_u32 v9, 0, v9, v2
	v_add_u32_e32 v2, 0xc00, v138
	v_lshrrev_b32_e32 v10, 4, v2
	v_lshlrev_b32_e32 v46, 3, v2
	v_bfe_u32 v2, v2, 4, 7
	v_and_b32_e32 v10, 0x7ffff80, v10
	v_mul_lo_u32 v10, v10, s2
	v_mul_u32_u24_e32 v2, 0x120, v2
	s_add_u32 s10, s72, 0x10f00
	v_add3_u32 v10, 0, v10, v2
	v_add_u32_e32 v2, 0xe00, v138
	s_addc_u32 s11, s73, 0
	v_lshrrev_b32_e32 v11, 4, v2
	s_add_u32 s20, s72, 0x25c00000
	v_and_b32_e32 v11, 0x7ffff80, v11
	v_and_b32_e32 v1, 15, v138
	s_addc_u32 s21, s73, 0
	v_lshlrev_b32_e32 v48, 3, v2
	v_bfe_u32 v2, v2, 4, 7
	v_mul_lo_u32 v11, v11, s2
	s_lshl_b32 s2, s79, 4
	v_mul_u32_u24_e32 v2, 0x120, v2
	v_lshrrev_b32_e32 v12, 4, v159
	v_and_or_b32 v13, s2, 48, v1
	v_readlane_b32 s2, v249, 35
	v_add3_u32 v11, 0, v11, v2
	s_mul_i32 s2, s2, 0x9000
	v_lshlrev_b32_e32 v2, 3, v12
	s_add_u32 s12, s72, 0x29d00000
	v_bfe_u32 v1, v138, 2, 2
	v_lshlrev_b32_e32 v34, 3, v138
	s_addc_u32 s13, s73, 0
	s_add_i32 s2, s2, 0
	v_or_b32_e32 v1, v2, v1
	v_readlane_b32 s48, v250, 26
	v_mov_b32_e32 v51, 0
	v_lshlrev_b32_e32 v52, 2, v12
	s_add_u32 s14, s72, 0x2bd00000
	v_and_b32_e32 v12, 24, v34
	v_mul_u32_u24_e32 v1, 0x120, v1
	v_and_b32_e32 v50, 48, v159
	v_readlane_b32 s56, v250, 34
	v_readlane_b32 s57, v250, 35
	v_readlane_b32 s28, v249, 13
	v_ashrrev_i32_e32 v35, 31, v34
	v_ashrrev_i32_e32 v37, 31, v36
	v_ashrrev_i32_e32 v39, 31, v38
	v_ashrrev_i32_e32 v41, 31, v40
	v_ashrrev_i32_e32 v43, 31, v42
	v_ashrrev_i32_e32 v45, 31, v44
	v_ashrrev_i32_e32 v47, 31, v46
	v_ashrrev_i32_e32 v49, 31, v48
	s_addc_u32 s15, s73, 0
	v_add3_u32 v1, s2, v12, v1
	v_lshl_add_u64 v[54:55], s[56:57], 0, v[50:51]
	v_lshlrev_b32_e32 v56, 9, v13
	s_mov_b64 s[4:5], 0
	s_add_i32 s22, 0, 0x22020
	s_movk_i32 s23, 0x1ff
	v_add_u32_e32 v53, v5, v3
	v_add_u32_e32 v57, v6, v3
	v_add_u32_e32 v63, v7, v3
	v_add_u32_e32 v66, v8, v3
	v_add_u32_e32 v67, v4, v3
	v_add_u32_e32 v68, v9, v3
	v_add_u32_e32 v69, v10, v3
	v_add_u32_e32 v70, v11, v3
	v_lshlrev_b32_e32 v58, 1, v2
	v_mov_b32_e32 v71, 0x358637bd
	s_mov_b32 s24, 0xf800000
	v_mov_b32_e32 v72, 0x260
	v_readlane_b32 s96, v249, 15
	v_readlane_b32 s29, v249, 14
	v_readlane_b32 s49, v250, 27
	v_readlane_b32 s50, v250, 28
	v_readlane_b32 s51, v250, 29
	v_readlane_b32 s52, v250, 30
	v_readlane_b32 s53, v250, 31
	v_readlane_b32 s54, v250, 32
	v_readlane_b32 s55, v250, 33
	v_readlane_b32 s58, v250, 36
	v_readlane_b32 s59, v250, 37
	v_readlane_b32 s60, v250, 38
	v_readlane_b32 s61, v250, 39
	v_readlane_b32 s62, v250, 40
	v_readlane_b32 s63, v250, 41
	global_load_dwordx4 v[160:163], v[54:55], off
	global_load_dwordx4 v[164:167], v[54:55], off offset:64
	global_load_dwordx4 v[168:171], v[54:55], off offset:128
	global_load_dwordx4 v[172:175], v[54:55], off offset:192
	global_load_dwordx4 v[176:179], v[54:55], off offset:256
	global_load_dwordx4 v[180:183], v[54:55], off offset:320
	global_load_dwordx4 v[184:187], v[54:55], off offset:384
	global_load_dwordx4 v[188:191], v[54:55], off offset:448
	v_mov_b32_e32 v137, 1
	s_mov_b32 s32, 0
	s_branch .LBB0_1688
.Lmy_hc_pf:
	s_waitcnt vmcnt(8)
	v_mov_b32_e32 v3, v136
	v_mov_b32_e32 v2, 0
	s_nop 0
	s_branch .Lmy_hc_join

; #define LAS __attribute__((address_space(3)))
; template <class Tp> DEV Tp* wsp(const Frame& F, size_t off) { return (Tp*)(F.ws + off); }
; DEV void hgrn_c_unit(Frame& F, int c, int hp) {
;     ...
;     { const bf16* HL = wsp<bf16>(F, WS_HL) + (size_t)(c * 4 + 2 * hp) * 16384;
; #pragma unroll
;       for (int j = 0; j < 8; ++j) { const int e8 = tid + 512 * j; const v4u v = *(const v4u*)(HL + 8 * e8); const int hh = e8 >> 11, rem = e8 & 2047, kr = rem >> 4, vc = (rem & 15) * 8;
;           *(LAS v4u*)(L + hh * 128 * HC_SROW + kr * HC_SROW + 2 * vc) = v; } }
;     __syncthreads();
;     const int h = 2 * hp + (w >> 2), ti = w & 3; const size_t row = (size_t)c * 64 + 16 * ti + n;
;     const LAS unsigned char* Sb = L + (w >> 2) * 128 * HC_SROW;
;     const bf16* qp = wsp<bf16>(F, WS_HQT) + row * 512 + h * 128 + 8 * q4;
;     f32x4 acc[8];
; #pragma unroll
;     for (int vt = 0; vt < 8; ++vt) acc[vt] = *(const f32x4*)(wsp<float>(F, WS_HIN) + row * 512 + h * 128 + 16 * vt + 4 * q4);
; #pragma unroll
;     for (int ks = 0; ks < 4; ++ks) { const ab8 qf = *(const ab8*)(qp + 32 * ks);
; #pragma unroll
;         for (int vt = 0; vt < 8; ++vt) { const ab8 sf = tr_frag(Sb, 32 * ks, 32 * vt, n, q4, HC_SROW); acc[vt] = __builtin_amdgcn_mfma_f32_16x16x32_bf16(sf, qf, acc[vt], 0, 0, 0); } }
;     ...
;     const bf16* HG = wsp<bf16>(F, WS_HG) + row * 512 + h * 128 + 4 * q4; bf16* OB = wsp<bf16>(F, WS_OB) + row * 512 + h * 128 + 4 * q4; const float* gn = ((const float*)F.A.in[20]) + 4 * q4;
; #pragma unroll
;     for (int vt = 0; vt < 8; ++vt) { const v2u gw_ = *(const v2u*)(HG + 16 * vt); const f32x4 g4 = *(const f32x4*)(gn + 16 * vt);
.LBB0_1686:
	s_ashr_i32 s4, s18, 1
	s_lshl_b32 s16, s18, 1
	s_lshl_b32 s5, s4, 2
	s_and_b32 s18, s16, 2
	s_or_b32 s16, s18, s5
	s_ashr_i32 s17, s16, 31
	s_lshl_b64 s[16:17], s[16:17], 15
	s_add_u32 s16, s20, s16
	s_addc_u32 s17, s21, s17
	v_lshl_add_u64 v[2:3], v[34:35], 1, s[16:17]
	v_lshl_add_u64 v[6:7], v[36:37], 1, s[16:17]
	v_lshl_add_u64 v[10:11], v[38:39], 1, s[16:17]
	v_lshl_add_u64 v[14:15], v[40:41], 1, s[16:17]
	v_lshl_add_u64 v[18:19], v[42:43], 1, s[16:17]
	v_lshl_add_u64 v[22:23], v[44:45], 1, s[16:17]
	v_lshl_add_u64 v[26:27], v[46:47], 1, s[16:17]
	v_lshl_add_u64 v[30:31], v[48:49], 1, s[16:17]
	global_load_dwordx4 v[2:5], v[2:3], off
	s_nop 0
	global_load_dwordx4 v[6:9], v[6:7], off
	s_nop 0
	global_load_dwordx4 v[10:13], v[10:11], off
	s_nop 0
	global_load_dwordx4 v[14:17], v[14:15], off
	s_nop 0
	global_load_dwordx4 v[18:21], v[18:19], off
	s_nop 0
	global_load_dwordx4 v[22:25], v[22:23], off
	s_nop 0
	global_load_dwordx4 v[26:29], v[26:27], off
	s_nop 0
	global_load_dwordx4 v[30:33], v[30:31], off
	v_readlane_b32 s5, v249, 35
	s_add_i32 s18, s18, s5
	s_ashr_i32 s5, s4, 31
	s_lshl_b64 s[4:5], s[4:5], 15
	s_lshl_b32 s18, s18, 7
	v_mov_b32_e32 v61, s5
	v_or_b32_e32 v60, s4, v56
	s_ashr_i32 s19, s18, 31
	v_lshl_add_u64 v[64:65], v[60:61], 2, s[12:13]
	v_lshlrev_b64 v[60:61], 1, v[60:61]
	s_lshl_b64 s[16:17], s[18:19], 1
	v_lshl_add_u64 v[74:75], s[14:15], 0, v[60:61]
	v_mov_b32_e32 v59, v51
	v_lshl_add_u64 v[74:75], v[74:75], 0, s[16:17]
	v_lshlrev_b32_e32 v50, 2, v52
	v_lshl_add_u64 v[64:65], s[18:19], 2, v[64:65]
	v_lshl_add_u64 v[98:99], v[74:75], 0, v[58:59]
	v_lshl_add_u64 v[64:65], v[64:65], 0, v[50:51]
	v_lshl_add_u64 v[132:133], s[6:7], 0, v[60:61]
	v_lshl_add_u64 v[132:133], v[132:133], 0, s[16:17]
	v_lshlrev_b32_e32 v134, 1, v52
	v_mov_b32_e32 v135, 0
	v_lshl_add_u64 v[132:133], v[132:133], 0, v[134:135]
	global_load_dwordx4 v[100:103], v[98:99], off
	global_load_dwordx4 v[104:107], v[98:99], off offset:64
	global_load_dwordx4 v[108:111], v[98:99], off offset:128
	global_load_dwordx4 v[112:115], v[98:99], off offset:192
	global_load_dwordx4 v[192:195], v[64:65], off
	global_load_dwordx4 v[196:199], v[64:65], off offset:64
	global_load_dwordx4 v[200:203], v[64:65], off offset:128
	global_load_dwordx4 v[204:207], v[64:65], off offset:192
	global_load_dwordx4 v[208:211], v[64:65], off offset:256
	global_load_dwordx4 v[212:215], v[64:65], off offset:320
	global_load_dwordx4 v[216:219], v[64:65], off offset:384
	global_load_dwordx4 v[220:223], v[64:65], off offset:448
	global_load_dwordx2 v[116:117], v[132:133], off
	global_load_dwordx2 v[118:119], v[132:133], off offset:32
	global_load_dwordx2 v[120:121], v[132:133], off offset:64
	global_load_dwordx2 v[122:123], v[132:133], off offset:96
	global_load_dwordx2 v[124:125], v[132:133], off offset:128
	global_load_dwordx2 v[126:127], v[132:133], off offset:160
	global_load_dwordx2 v[128:129], v[132:133], off offset:192
	global_load_dwordx2 v[130:131], v[132:133], off offset:224
	s_waitcnt vmcnt(27)
	ds_write_b128 v53, v[2:5]
	s_waitcnt vmcnt(26)
	ds_write_b128 v57, v[6:9]
	s_waitcnt vmcnt(25)
	ds_write_b128 v63, v[10:13]
	s_waitcnt vmcnt(24)
	ds_write_b128 v66, v[14:17]
	s_waitcnt vmcnt(23)
	ds_write_b128 v67, v[18:21]
	s_waitcnt vmcnt(22)
	ds_write_b128 v68, v[22:25]
	s_waitcnt vmcnt(21)
	ds_write_b128 v69, v[26:29]
	s_waitcnt vmcnt(20)
	ds_write_b128 v70, v[30:33]
	s_waitcnt lgkmcnt(0)
	s_barrier
	s_waitcnt vmcnt(8)
	ds_read_b64_tr_b16 v[16:17], v1 offset:1152
	ds_read_b64_tr_b16 v[14:15], v1
	ds_read_b64_tr_b16 v[28:29], v1 offset:1184
	ds_read_b64_tr_b16 v[26:27], v1 offset:32
	ds_read_b64_tr_b16 v[30:31], v1 offset:64
	ds_read_b64_tr_b16 v[74:75], v1 offset:96
	ds_read_b64_tr_b16 v[32:33], v1 offset:1216
	ds_read_b64_tr_b16 v[76:77], v1 offset:1248
	ds_read_b64_tr_b16 v[82:83], v1 offset:128
	s_waitcnt lgkmcnt(7)
	v_mfma_f32_16x16x32_bf16 v[6:9], v[14:17], v[100:103], v[192:195]
	s_waitcnt lgkmcnt(5)
	v_mfma_f32_16x16x32_bf16 v[10:13], v[26:29], v[100:103], v[196:199]
	s_waitcnt lgkmcnt(2)
	v_mfma_f32_16x16x32_bf16 v[18:21], v[30:33], v[100:103], v[200:203]
	ds_read_b64_tr_b16 v[84:85], v1 offset:1280
	ds_read_b64_tr_b16 v[32:33], v1 offset:1312
	s_waitcnt lgkmcnt(3)
	v_mfma_f32_16x16x32_bf16 v[22:25], v[74:77], v[100:103], v[204:207]
	ds_read_b64_tr_b16 v[30:31], v1 offset:160
	ds_read_b64_tr_b16 v[74:75], v1 offset:192
	ds_read_b64_tr_b16 v[86:87], v1 offset:224
	ds_read_b64_tr_b16 v[76:77], v1 offset:1344
	ds_read_b64_tr_b16 v[88:89], v1 offset:1376
	ds_read_b64_tr_b16 v[90:91], v1 offset:9216
	s_waitcnt lgkmcnt(7)
	v_mfma_f32_16x16x32_bf16 v[14:17], v[82:85], v[100:103], v[208:211]
	s_waitcnt lgkmcnt(5)
	v_mfma_f32_16x16x32_bf16 v[26:29], v[30:33], v[100:103], v[212:215]
	s_waitcnt lgkmcnt(2)
	v_mfma_f32_16x16x32_bf16 v[74:77], v[74:77], v[100:103], v[216:219]
	ds_read_b64_tr_b16 v[92:93], v1 offset:10368
	s_nop 1
	ds_read_b64_tr_b16 v[84:85], v1 offset:10400
	s_waitcnt lgkmcnt(3)
	v_mfma_f32_16x16x32_bf16 v[2:5], v[86:89], v[100:103], v[220:223]
	ds_read_b64_tr_b16 v[82:83], v1 offset:9248
	s_nop 1
	ds_read_b64_tr_b16 v[30:31], v1 offset:9280
	ds_read_b64_tr_b16 v[86:87], v1 offset:9312
	ds_read_b64_tr_b16 v[32:33], v1 offset:10432
	ds_read_b64_tr_b16 v[88:89], v1 offset:10464
	s_waitcnt lgkmcnt(4)
	v_mfma_f32_16x16x32_bf16 v[10:13], v[82:85], v[104:107], v[10:13]
	ds_read_b64_tr_b16 v[82:83], v1 offset:9344
	ds_read_b64_tr_b16 v[84:85], v1 offset:10496
	v_mfma_f32_16x16x32_bf16 v[6:9], v[90:93], v[104:107], v[6:9]
	s_waitcnt lgkmcnt(3)
; DEV void p3_phase(Frame& F, bool do_scan, int qoff) {
;     ...
;             if (F.tid == 0) *qslot = (int)atomicAdd(cctr, 1u);
; DEV void hgrn_c_unit(Frame& F, int c, int hp) {
;     ...
;     for (int ks = 0; ks < 4; ++ks) { const ab8 qf = *(const ab8*)(qp + 32 * ks);
; #pragma unroll
;         for (int vt = 0; vt < 8; ++vt) { const ab8 sf = tr_frag(Sb, 32 * ks, 32 * vt, n, q4, HC_SROW); acc[vt] = __builtin_amdgcn_mfma_f32_16x16x32_bf16(sf, qf, acc[vt], 0, 0, 0); } }
;     float ss = 0.f;
; #pragma unroll
;     for (int vt = 0; vt < 8; ++vt) ss += (acc[vt][0] * acc[vt][0] + acc[vt][1] * acc[vt][1]) + (acc[vt][2] * acc[vt][2] + acc[vt][3] * acc[vt][3]);
;     ss += __shfl_xor(ss, 16); ss += __shfl_xor(ss, 32);
;     const float rr = 1.0f / sqrtf(ss * (1.f / 128.f) + EPS);
	v_mfma_f32_16x16x32_bf16 v[18:21], v[30:33], v[104:107], v[18:21]
	ds_read_b64_tr_b16 v[30:31], v1 offset:9376
	ds_read_b64_tr_b16 v[90:91], v1 offset:9408
	ds_read_b64_tr_b16 v[94:95], v1 offset:9440
	ds_read_b64_tr_b16 v[32:33], v1 offset:10528
	ds_read_b64_tr_b16 v[92:93], v1 offset:10560
	ds_read_b64_tr_b16 v[96:97], v1 offset:10592
	s_waitcnt lgkmcnt(6)
	v_mfma_f32_16x16x32_bf16 v[14:17], v[82:85], v[104:107], v[14:17]
	v_mfma_f32_16x16x32_bf16 v[22:25], v[86:89], v[104:107], v[22:25]
	s_waitcnt lgkmcnt(2)
	v_mfma_f32_16x16x32_bf16 v[26:29], v[30:33], v[104:107], v[26:29]
	ds_read_b64_tr_b16 v[30:31], v1 offset:18432
	s_waitcnt lgkmcnt(2)
	v_mfma_f32_16x16x32_bf16 v[74:77], v[90:93], v[104:107], v[74:77]
	ds_read_b64_tr_b16 v[32:33], v1 offset:19584
	ds_read_b64_tr_b16 v[92:93], v1 offset:19616
	s_waitcnt lgkmcnt(3)
	v_mfma_f32_16x16x32_bf16 v[2:5], v[94:97], v[104:107], v[2:5]
	ds_read_b64_tr_b16 v[90:91], v1 offset:18464
	ds_read_b64_tr_b16 v[78:79], v1 offset:18496
	ds_read_b64_tr_b16 v[94:95], v1 offset:18528
	ds_read_b64_tr_b16 v[80:81], v1 offset:19648
	ds_read_b64_tr_b16 v[96:97], v1 offset:19680
	s_waitcnt lgkmcnt(6)
	v_mfma_f32_16x16x32_bf16 v[6:9], v[30:33], v[108:111], v[6:9]
	ds_read_b64_tr_b16 v[30:31], v1 offset:18560
	s_waitcnt lgkmcnt(2)
	v_mfma_f32_16x16x32_bf16 v[18:21], v[78:81], v[108:111], v[18:21]
	ds_read_b64_tr_b16 v[32:33], v1 offset:19712
	ds_read_b64_tr_b16 v[80:81], v1 offset:19744
	v_mfma_f32_16x16x32_bf16 v[10:13], v[90:93], v[108:111], v[10:13]
	s_waitcnt lgkmcnt(3)
	v_mfma_f32_16x16x32_bf16 v[90:93], v[94:97], v[108:111], v[22:25]
	ds_read_b64_tr_b16 v[78:79], v1 offset:18592
	s_nop 1
	ds_read_b64_tr_b16 v[22:23], v1 offset:18624
	ds_read_b64_tr_b16 v[94:95], v1 offset:18656
	ds_read_b64_tr_b16 v[24:25], v1 offset:19776
	ds_read_b64_tr_b16 v[96:97], v1 offset:19808
	s_waitcnt lgkmcnt(4)
	v_mfma_f32_16x16x32_bf16 v[78:81], v[78:81], v[108:111], v[26:29]
	s_nop 2
	ds_read_b64_tr_b16 v[26:27], v1 offset:27648
	s_waitcnt lgkmcnt(2)
	v_mfma_f32_16x16x32_bf16 v[74:77], v[22:25], v[108:111], v[74:77]
	ds_read_b64_tr_b16 v[28:29], v1 offset:28800
	ds_read_b64_tr_b16 v[24:25], v1 offset:28832
	v_mfma_f32_16x16x32_bf16 v[14:17], v[30:33], v[108:111], v[14:17]
	s_waitcnt lgkmcnt(3)
	v_mfma_f32_16x16x32_bf16 v[2:5], v[94:97], v[108:111], v[2:5]
	ds_read_b64_tr_b16 v[22:23], v1 offset:27680
	ds_read_b64_tr_b16 v[82:83], v1 offset:27712
	ds_read_b64_tr_b16 v[94:95], v1 offset:27744
	ds_read_b64_tr_b16 v[84:85], v1 offset:28864
	ds_read_b64_tr_b16 v[96:97], v1 offset:28896
	s_waitcnt lgkmcnt(6)
	v_mfma_f32_16x16x32_bf16 v[30:33], v[26:29], v[112:115], v[6:9]
	s_nop 2
	ds_read_b64_tr_b16 v[6:7], v1 offset:27776
	s_waitcnt lgkmcnt(5)
	v_mfma_f32_16x16x32_bf16 v[26:29], v[22:25], v[112:115], v[10:13]
	ds_read_b64_tr_b16 v[8:9], v1 offset:28928
	s_nop 1
	ds_read_b64_tr_b16 v[12:13], v1 offset:28960
	v_mov_b32_e32 v64, v30
	s_nop 2
	v_mov_b32_e32 v65, v26
	s_waitcnt lgkmcnt(4)
	v_mfma_f32_16x16x32_bf16 v[22:25], v[82:85], v[112:115], v[18:21]
	s_waitcnt lgkmcnt(3)
	v_mfma_f32_16x16x32_bf16 v[18:21], v[94:97], v[112:115], v[90:93]
	ds_read_b64_tr_b16 v[10:11], v1 offset:27808
	ds_read_b64_tr_b16 v[82:83], v1 offset:27840
	s_nop 0
	ds_read_b64_tr_b16 v[90:91], v1 offset:27872
	ds_read_b64_tr_b16 v[84:85], v1 offset:28992
	ds_read_b64_tr_b16 v[92:93], v1 offset:29024
	s_nop 1
	v_mul_f32_e32 v50, v19, v19
	s_waitcnt lgkmcnt(6)
	v_mfma_f32_16x16x32_bf16 v[14:17], v[6:9], v[112:115], v[14:17]
	s_waitcnt lgkmcnt(4)
	v_mfma_f32_16x16x32_bf16 v[10:13], v[10:13], v[112:115], v[78:81]
	s_waitcnt lgkmcnt(1)
	v_mfma_f32_16x16x32_bf16 v[6:9], v[82:85], v[112:115], v[74:77]
	s_nop 0
	v_mov_b32_e32 v78, v33
	v_mov_b32_e32 v79, v29
	v_pk_mul_f32 v[80:81], v[24:25], v[24:25]
	v_mov_b32_e32 v74, v31
	v_mov_b32_e32 v75, v27
	v_mov_b32_e32 v76, v32
	v_mov_b32_e32 v77, v28
	v_pk_mul_f32 v[82:83], v[22:23], v[22:23]
	v_pk_mul_f32 v[74:75], v[74:75], v[74:75]
	v_pk_mul_f32 v[78:79], v[78:79], v[78:79]
	v_pk_mov_b32 v[84:85], v[82:83], v[80:81] op_sel:[1,0]
	v_mov_b32_e32 v83, v81
	v_pk_fma_f32 v[64:65], v[64:65], v[64:65], v[74:75]
	v_pk_fma_f32 v[74:75], v[76:77], v[76:77], v[78:79]
	v_pk_add_f32 v[76:77], v[84:85], v[82:83]
	v_pk_add_f32 v[64:65], v[64:65], v[74:75]
	v_mul_f32_e32 v59, v14, v14
	v_mul_f32_e32 v62, v15, v15
	v_pk_add_f32 v[74:75], v[76:77], v[76:77] op_sel:[0,1] op_sel_hi:[1,0]
	v_pk_add_f32 v[64:65], v[64:65], v[64:65] op_sel:[0,1] op_sel_hi:[1,0]
	v_pk_fma_f32 v[80:81], v[18:19], v[18:19], v[50:51] op_sel_hi:[1,1,0]
	v_mov_b32_e32 v75, v62
	v_mov_b32_e32 v65, v59
	v_mul_f32_e32 v50, v21, v21
	s_waitcnt lgkmcnt(0)
	v_mfma_f32_16x16x32_bf16 v[2:5], v[90:93], v[112:115], v[2:5]
	s_waitcnt vmcnt(0)
	s_and_saveexec_b64 s[34:35], s[0:1]
	global_atomic_add v136, v51, v137, s[10:11] sc0
	s_mov_b64 exec, s[34:35]
	s_mov_b32 s32, 1
	v_mul_f32_e32 v73, v16, v16
	v_mul_f32_e32 v86, v17, v17
	v_pk_add_f32 v[64:65], v[64:65], v[74:75]
	v_pk_fma_f32 v[74:75], v[20:21], v[20:21], v[50:51] op_sel_hi:[1,1,0]
	v_mov_b32_e32 v81, v73
	v_mov_b32_e32 v75, v86
	v_pk_add_f32 v[74:75], v[80:81], v[74:75]
	s_nop 0
	v_mul_f32_e32 v50, v2, v2
	v_pk_add_f32 v[64:65], v[64:65], v[74:75]
	v_pk_mul_f32 v[74:75], v[12:13], v[12:13]
	v_pk_add_f32 v[80:81], v[64:65], v[64:65] op_sel:[0,1] op_sel_hi:[1,0]
	v_pk_mul_f32 v[76:77], v[10:11], v[10:11]
	v_mov_b32_e32 v81, v50
	v_lshlrev_b32_e32 v50, 1, v52
	v_pk_mov_b32 v[78:79], v[76:77], v[74:75] op_sel:[1,0]
	v_mov_b32_e32 v77, v75
	v_pk_add_f32 v[78:79], v[78:79], v[76:77]
	v_mul_f32_e32 v59, v3, v3
	v_pk_add_f32 v[78:79], v[78:79], v[78:79] op_sel:[0,1] op_sel_hi:[1,0]
	v_mul_f32_e32 v62, v7, v7
	v_mov_b32_e32 v79, v59
	v_mul_f32_e32 v73, v4, v4
	v_pk_add_f32 v[78:79], v[80:81], v[78:79]
	v_pk_fma_f32 v[80:81], v[6:7], v[6:7], v[62:63] op_sel_hi:[1,1,0]
	v_mul_f32_e32 v62, v9, v9
	v_mul_f32_e32 v86, v5, v5
	v_mov_b32_e32 v81, v73
	v_pk_fma_f32 v[84:85], v[8:9], v[8:9], v[62:63] op_sel_hi:[1,1,0]
	v_and_b32_e32 v73, 64, v139
	v_mov_b32_e32 v85, v86
	v_xor_b32_e32 v62, 16, v139
	v_add_u32_e32 v73, 64, v73
	v_pk_add_f32 v[80:81], v[80:81], v[84:85]
	v_cmp_lt_i32_e32 vcc, v62, v73
	v_pk_add_f32 v[78:79], v[78:79], v[80:81]
	v_lshl_add_u64 v[60:61], s[8:9], 0, v[60:61]
	v_cndmask_b32_e32 v62, v139, v62, vcc
	v_add_f32_e32 v59, v78, v79
	v_lshlrev_b32_e32 v62, 2, v62
	ds_bpermute_b32 v62, v62, v59
	v_lshl_add_u64 v[60:61], v[60:61], 0, s[16:17]
	v_lshl_add_u64 v[60:61], v[60:61], 0, v[50:51]
	s_waitcnt lgkmcnt(0)
; DEV unsigned cvtpk(float lo, float hi) { typedef float f2 __attribute__((ext_vector_type(2))); typedef __bf16 b2 __attribute__((ext_vector_type(2))); f2 v = {lo, hi}; b2 b = __builtin_convertvector(v, b2); return __builtin_bit_cast(unsigned, b); }
; template <class Tp> DEV Tp* wsp(const Frame& F, size_t off) { return (Tp*)(F.ws + off); }
; DEV void hgrn_c_unit(Frame& F, int c, int hp) {
;     ...
;     float ss = 0.f;
; #pragma unroll
;     for (int vt = 0; vt < 8; ++vt) ss += (acc[vt][0] * acc[vt][0] + acc[vt][1] * acc[vt][1]) + (acc[vt][2] * acc[vt][2] + acc[vt][3] * acc[vt][3]);
;     ss += __shfl_xor(ss, 16); ss += __shfl_xor(ss, 32);
;     const float rr = 1.0f / sqrtf(ss * (1.f / 128.f) + EPS);
;     const bf16* HG = wsp<bf16>(F, WS_HG) + row * 512 + h * 128 + 4 * q4; bf16* OB = wsp<bf16>(F, WS_OB) + row * 512 + h * 128 + 4 * q4; const float* gn = ((const float*)F.A.in[20]) + 4 * q4;
; #pragma unroll
;     for (int vt = 0; vt < 8; ++vt) { const v2u gw_ = *(const v2u*)(HG + 16 * vt); const f32x4 g4 = *(const f32x4*)(gn + 16 * vt);
;         v2u wv; wv.x = cvtpk(acc[vt][0] * rr * g4[0] * bflo(gw_.x), acc[vt][1] * rr * g4[1] * bfhi(gw_.x)); wv.y = cvtpk(acc[vt][2] * rr * g4[2] * bflo(gw_.y), acc[vt][3] * rr * g4[3] * bfhi(gw_.y));
;         *(v2u*)(OB + 16 * vt) = wv; }
;     __syncthreads();
	v_add_f32_e32 v59, v59, v62
	v_xor_b32_e32 v62, 32, v139
	v_cmp_lt_i32_e32 vcc, v62, v73
	v_cndmask_b32_e32 v62, v139, v62, vcc
	v_lshlrev_b32_e32 v62, 2, v62
	ds_bpermute_b32 v62, v62, v59
	s_waitcnt lgkmcnt(0)
	v_add_f32_e32 v59, v59, v62
	v_fmamk_f32 v59, v59, 0x3c000000, v71
	v_mul_f32_e32 v62, 0x4f800000, v59
	v_cmp_gt_f32_e32 vcc, s24, v59
	s_nop 1
	v_cndmask_b32_e32 v59, v59, v62, vcc
	v_sqrt_f32_e32 v62, v59
	s_nop 0
	v_add_u32_e32 v73, -1, v62
	v_fma_f32 v78, -v73, v62, v59
	v_cmp_ge_f32_e64 s[4:5], 0, v78
	v_add_u32_e32 v78, 1, v62
	s_nop 0
	v_cndmask_b32_e64 v73, v62, v73, s[4:5]
	v_fma_f32 v62, -v78, v62, v59
	v_cmp_lt_f32_e64 s[4:5], 0, v62
	s_nop 1
	v_cndmask_b32_e64 v62, v73, v78, s[4:5]
	v_mul_f32_e32 v73, 0x37800000, v62
	v_cndmask_b32_e32 v62, v62, v73, vcc
	v_cmp_class_f32_e32 vcc, v59, v72
	s_nop 1
	v_cndmask_b32_e32 v59, v62, v59, vcc
	v_div_scale_f32 v62, s[4:5], v59, v59, 1.0
	v_rcp_f32_e32 v73, v62
	s_mov_b64 s[4:5], -1
	v_fma_f32 v78, -v62, v73, 1.0
	v_fmac_f32_e32 v73, v78, v73
	v_div_scale_f32 v78, vcc, 1.0, v59, 1.0
	v_mul_f32_e32 v79, v78, v73
	v_fma_f32 v80, -v62, v79, v78
	v_fmac_f32_e32 v79, v80, v73
	v_fma_f32 v62, -v62, v79, v78
	v_div_fmas_f32 v62, v62, v73, v79
	v_div_fixup_f32 v62, v62, v59, 1.0
	v_pk_mul_f32 v[30:31], v[30:31], v[62:63] op_sel_hi:[1,0]
	v_pk_mul_f32 v[32:33], v[32:33], v[62:63] op_sel_hi:[1,0]
	v_lshlrev_b32_e32 v140, 16, v116
	v_and_b32_e32 v141, 0xffff0000, v116
	v_lshlrev_b32_e32 v142, 16, v117
	v_and_b32_e32 v143, 0xffff0000, v117
	v_pk_mul_f32 v[30:31], v[160:161], v[30:31]
	v_pk_mul_f32 v[32:33], v[162:163], v[32:33]
	v_pk_mul_f32 v[30:31], v[30:31], v[140:141]
	v_pk_mul_f32 v[32:33], v[32:33], v[142:143]
	v_cvt_pk_bf16_f32 v30, v30, v31
	v_cvt_pk_bf16_f32 v31, v32, v33
	global_store_dwordx2 v[60:61], v[30:31], off
	v_pk_mul_f32 v[26:27], v[26:27], v[62:63] op_sel_hi:[1,0]
	v_pk_mul_f32 v[28:29], v[28:29], v[62:63] op_sel_hi:[1,0]
	v_lshlrev_b32_e32 v144, 16, v118
	v_and_b32_e32 v145, 0xffff0000, v118
	v_lshlrev_b32_e32 v146, 16, v119
	v_and_b32_e32 v147, 0xffff0000, v119
	v_pk_mul_f32 v[26:27], v[164:165], v[26:27]
	v_pk_mul_f32 v[28:29], v[166:167], v[28:29]
	v_pk_mul_f32 v[26:27], v[26:27], v[144:145]
	v_pk_mul_f32 v[28:29], v[28:29], v[146:147]
	v_cvt_pk_bf16_f32 v26, v26, v27
	v_cvt_pk_bf16_f32 v27, v28, v29
	global_store_dwordx2 v[60:61], v[26:27], off offset:32
	v_pk_mul_f32 v[22:23], v[22:23], v[62:63] op_sel_hi:[1,0]
	v_pk_mul_f32 v[24:25], v[24:25], v[62:63] op_sel_hi:[1,0]
	v_lshlrev_b32_e32 v140, 16, v120
	v_and_b32_e32 v141, 0xffff0000, v120
	v_lshlrev_b32_e32 v142, 16, v121
	v_and_b32_e32 v143, 0xffff0000, v121
	v_pk_mul_f32 v[22:23], v[168:169], v[22:23]
	v_pk_mul_f32 v[24:25], v[170:171], v[24:25]
	v_pk_mul_f32 v[22:23], v[22:23], v[140:141]
	v_pk_mul_f32 v[24:25], v[24:25], v[142:143]
	v_cvt_pk_bf16_f32 v22, v22, v23
	v_cvt_pk_bf16_f32 v23, v24, v25
	global_store_dwordx2 v[60:61], v[22:23], off offset:64
	v_pk_mul_f32 v[18:19], v[18:19], v[62:63] op_sel_hi:[1,0]
	v_pk_mul_f32 v[20:21], v[20:21], v[62:63] op_sel_hi:[1,0]
	v_lshlrev_b32_e32 v144, 16, v122
	v_and_b32_e32 v145, 0xffff0000, v122
	v_lshlrev_b32_e32 v146, 16, v123
	v_and_b32_e32 v147, 0xffff0000, v123
	v_pk_mul_f32 v[18:19], v[172:173], v[18:19]
	v_pk_mul_f32 v[20:21], v[174:175], v[20:21]
	v_pk_mul_f32 v[18:19], v[18:19], v[144:145]
	v_pk_mul_f32 v[20:21], v[20:21], v[146:147]
	v_cvt_pk_bf16_f32 v18, v18, v19
	v_cvt_pk_bf16_f32 v19, v20, v21
	global_store_dwordx2 v[60:61], v[18:19], off offset:96
	v_pk_mul_f32 v[14:15], v[14:15], v[62:63] op_sel_hi:[1,0]
	v_pk_mul_f32 v[16:17], v[16:17], v[62:63] op_sel_hi:[1,0]
	v_lshlrev_b32_e32 v140, 16, v124
	v_and_b32_e32 v141, 0xffff0000, v124
	v_lshlrev_b32_e32 v142, 16, v125
	v_and_b32_e32 v143, 0xffff0000, v125
	v_pk_mul_f32 v[14:15], v[176:177], v[14:15]
	v_pk_mul_f32 v[16:17], v[178:179], v[16:17]
	v_pk_mul_f32 v[14:15], v[14:15], v[140:141]
	v_pk_mul_f32 v[16:17], v[16:17], v[142:143]
	v_cvt_pk_bf16_f32 v14, v14, v15
	v_cvt_pk_bf16_f32 v15, v16, v17
	global_store_dwordx2 v[60:61], v[14:15], off offset:128
	v_pk_mul_f32 v[10:11], v[10:11], v[62:63] op_sel_hi:[1,0]
	v_pk_mul_f32 v[12:13], v[12:13], v[62:63] op_sel_hi:[1,0]
	v_lshlrev_b32_e32 v144, 16, v126
	v_and_b32_e32 v145, 0xffff0000, v126
	v_lshlrev_b32_e32 v146, 16, v127
	v_and_b32_e32 v147, 0xffff0000, v127
	v_pk_mul_f32 v[10:11], v[180:181], v[10:11]
	v_pk_mul_f32 v[12:13], v[182:183], v[12:13]
	v_pk_mul_f32 v[10:11], v[10:11], v[144:145]
	v_pk_mul_f32 v[12:13], v[12:13], v[146:147]
	v_cvt_pk_bf16_f32 v10, v10, v11
	v_cvt_pk_bf16_f32 v11, v12, v13
	global_store_dwordx2 v[60:61], v[10:11], off offset:160
	v_pk_mul_f32 v[6:7], v[6:7], v[62:63] op_sel_hi:[1,0]
	v_pk_mul_f32 v[8:9], v[8:9], v[62:63] op_sel_hi:[1,0]
	v_lshlrev_b32_e32 v140, 16, v128
	v_and_b32_e32 v141, 0xffff0000, v128
	v_lshlrev_b32_e32 v142, 16, v129
	v_and_b32_e32 v143, 0xffff0000, v129
	v_pk_mul_f32 v[6:7], v[184:185], v[6:7]
	v_pk_mul_f32 v[8:9], v[186:187], v[8:9]
	v_pk_mul_f32 v[6:7], v[6:7], v[140:141]
	v_pk_mul_f32 v[8:9], v[8:9], v[142:143]
	v_cvt_pk_bf16_f32 v6, v6, v7
	v_cvt_pk_bf16_f32 v7, v8, v9
	global_store_dwordx2 v[60:61], v[6:7], off offset:192
	v_pk_mul_f32 v[2:3], v[2:3], v[62:63] op_sel_hi:[1,0]
	v_pk_mul_f32 v[4:5], v[4:5], v[62:63] op_sel_hi:[1,0]
	v_lshlrev_b32_e32 v144, 16, v130
	v_and_b32_e32 v145, 0xffff0000, v130
	v_lshlrev_b32_e32 v146, 16, v131
	v_and_b32_e32 v147, 0xffff0000, v131
	v_pk_mul_f32 v[2:3], v[188:189], v[2:3]
	v_pk_mul_f32 v[4:5], v[190:191], v[4:5]
	v_pk_mul_f32 v[2:3], v[2:3], v[144:145]
	v_pk_mul_f32 v[4:5], v[4:5], v[146:147]
	v_cvt_pk_bf16_f32 v2, v2, v3
	v_cvt_pk_bf16_f32 v3, v4, v5
	global_store_dwordx2 v[60:61], v[2:3], off offset:224
	s_barrier

; DEV void p3_phase(Frame& F, bool do_scan, int qoff) {
;     ...
;         for (;;) {
;             if (F.tid == 0) *qslot = (int)atomicAdd(cctr, 1u);
.LBB0_1688:
	s_and_saveexec_b64 s[2:3], s[0:1]
	s_cbranch_execz .LBB0_1692
	s_cmp_lg_u32 s32, 0
	s_cbranch_scc1 .Lmy_hc_pf
	s_mov_b64 s[18:19], exec
	v_mbcnt_lo_u32_b32 v2, s18, 0
	v_mbcnt_hi_u32_b32 v2, s19, v2
	v_cmp_eq_u32_e32 vcc, 0, v2
	s_and_saveexec_b64 s[16:17], vcc
	s_cbranch_execz .LBB0_1691
	s_bcnt1_i32_b64 s18, s[18:19]
	v_mov_b32_e32 v3, s18
	global_atomic_add v3, v51, v3, s[10:11] sc0

; DEV void p3_phase(Frame& F, bool do_scan, int qoff) {
;     ...
;             if (F.tid == 0) *qslot = (int)atomicAdd(cctr, 1u);
;             __syncthreads();
.Lmy_hc_join:
	v_readfirstlane_b32 s16, v3
	v_mov_b32_e32 v3, s22
	s_nop 0
	v_add_u32_e32 v2, s16, v2
	ds_write_b32 v3, v2
